# residual epilogue (out-proj/FFN-out): 16 residual loads in flight with counted vmcnt instead of 32 load-wait-store round trips
# speedup vs baseline: 1.0429x; 1.0003x over previous
.LBB0_679:
	v_lshl_add_u32 v168, s22, 8, v3
	v_lshl_or_b32 v166, s28, 8, v171
	s_ashr_i32 s10, s22, 3
	v_ashrrev_i32_e32 v167, 31, v166
	s_mul_hi_i32 s11, s10, 0x18000
	s_mul_i32 s10, s10, 0x18000
	s_add_u32 s10, s2, s10
	s_addc_u32 s11, s3, s11
	v_lshl_add_u64 v[128:129], v[166:167], 2, s[10:11]
	v_lshl_add_u32 v173, v168, 10, v166
	v_lshlrev_b32_e32 v173, 2, v173
	v_mov_b32_e32 v174, v173
	global_load_dwordx4 v[144:147], v[128:129], off
	global_load_dwordx4 v[136:139], v[128:129], off offset:64
	global_load_dwordx4 v[132:135], v[128:129], off offset:512
	s_nop 0
	global_load_dwordx4 v[128:131], v[128:129], off offset:576
	s_and_b64 vcc, exec, s[38:39]
	s_mov_b32 s23, 0xffff
	global_load_dwordx4 v[190:193], v173, s[42:43]
	global_load_dwordx4 v[194:197], v173, s[42:43] offset:64
	global_load_dwordx4 v[198:201], v173, s[42:43] offset:512
	global_load_dwordx4 v[202:205], v173, s[42:43] offset:576
	v_add_u32_e32 v173, 0x10000, v173
	global_load_dwordx4 v[206:209], v173, s[42:43]
	global_load_dwordx4 v[210:213], v173, s[42:43] offset:64
	global_load_dwordx4 v[214:217], v173, s[42:43] offset:512
	global_load_dwordx4 v[218:221], v173, s[42:43] offset:576
	v_add_u32_e32 v173, 0x10000, v173
	global_load_dwordx4 v[222:225], v173, s[42:43]
	global_load_dwordx4 v[226:229], v173, s[42:43] offset:64
	global_load_dwordx4 v[230:233], v173, s[42:43] offset:512
	global_load_dwordx4 v[234:237], v173, s[42:43] offset:576
	v_add_u32_e32 v173, 0x10000, v173
	global_load_dwordx4 v[238:241], v173, s[42:43]
	global_load_dwordx4 v[242:245], v173, s[42:43] offset:64
	global_load_dwordx4 v[246:249], v173, s[42:43] offset:512
	global_load_dwordx4 v[164:167], v173, s[42:43] offset:576
	s_waitcnt vmcnt(15)
	v_pk_fma_f32 v[142:143], v[142:143], v[146:147], v[192:193]
	v_pk_fma_f32 v[140:141], v[140:141], v[144:145], v[190:191]
	global_store_dwordx4 v174, v[140:143], s[60:61]
	v_add_u32_e32 v173, 0x50000, v173
	global_load_dwordx4 v[190:193], v173, s[42:43]
	s_waitcnt vmcnt(16)
	v_pk_fma_f32 v[126:127], v[126:127], v[138:139], v[196:197]
	v_pk_fma_f32 v[124:125], v[124:125], v[136:137], v[194:195]
	global_store_dwordx4 v174, v[124:127], s[60:61] offset:64
	global_load_dwordx4 v[194:197], v173, s[42:43] offset:64
	s_waitcnt vmcnt(17)
	v_pk_fma_f32 v[122:123], v[122:123], v[134:135], v[200:201]
	v_pk_fma_f32 v[120:121], v[120:121], v[132:133], v[198:199]
	global_store_dwordx4 v174, v[120:123], s[60:61] offset:512
	global_load_dwordx4 v[198:201], v173, s[42:43] offset:512
	s_waitcnt vmcnt(18)
	v_pk_fma_f32 v[118:119], v[118:119], v[130:131], v[204:205]
	v_pk_fma_f32 v[116:117], v[116:117], v[128:129], v[202:203]
	global_store_dwordx4 v174, v[116:119], s[60:61] offset:576
	global_load_dwordx4 v[202:205], v173, s[42:43] offset:576
	v_add_u32_e32 v174, 0x10000, v174
	s_waitcnt vmcnt(19)
	v_pk_fma_f32 v[114:115], v[114:115], v[146:147], v[208:209]
	v_pk_fma_f32 v[112:113], v[112:113], v[144:145], v[206:207]
	global_store_dwordx4 v174, v[112:115], s[60:61]
	v_add_u32_e32 v173, 0x10000, v173
	global_load_dwordx4 v[206:209], v173, s[42:43]
	s_waitcnt vmcnt(20)
	v_pk_fma_f32 v[110:111], v[110:111], v[138:139], v[212:213]
	v_pk_fma_f32 v[108:109], v[108:109], v[136:137], v[210:211]
	global_store_dwordx4 v174, v[108:111], s[60:61] offset:64
	global_load_dwordx4 v[210:213], v173, s[42:43] offset:64
	s_waitcnt vmcnt(21)
	v_pk_fma_f32 v[106:107], v[106:107], v[134:135], v[216:217]
	v_pk_fma_f32 v[104:105], v[104:105], v[132:133], v[214:215]
	global_store_dwordx4 v174, v[104:107], s[60:61] offset:512
	global_load_dwordx4 v[214:217], v173, s[42:43] offset:512
	s_waitcnt vmcnt(22)
	v_pk_fma_f32 v[102:103], v[102:103], v[130:131], v[220:221]
	v_pk_fma_f32 v[100:101], v[100:101], v[128:129], v[218:219]
	global_store_dwordx4 v174, v[100:103], s[60:61] offset:576
	global_load_dwordx4 v[218:221], v173, s[42:43] offset:576
	v_add_u32_e32 v174, 0x10000, v174
	s_waitcnt vmcnt(23)
	v_pk_fma_f32 v[98:99], v[98:99], v[146:147], v[224:225]
	v_pk_fma_f32 v[96:97], v[96:97], v[144:145], v[222:223]
	global_store_dwordx4 v174, v[96:99], s[60:61]
	v_add_u32_e32 v173, 0x10000, v173
	global_load_dwordx4 v[222:225], v173, s[42:43]
	s_waitcnt vmcnt(24)
	v_pk_fma_f32 v[94:95], v[94:95], v[138:139], v[228:229]
	v_pk_fma_f32 v[92:93], v[92:93], v[136:137], v[226:227]
	global_store_dwordx4 v174, v[92:95], s[60:61] offset:64
	global_load_dwordx4 v[226:229], v173, s[42:43] offset:64
	s_waitcnt vmcnt(25)
	v_pk_fma_f32 v[90:91], v[90:91], v[134:135], v[232:233]
	v_pk_fma_f32 v[88:89], v[88:89], v[132:133], v[230:231]
	global_store_dwordx4 v174, v[88:91], s[60:61] offset:512
	global_load_dwordx4 v[230:233], v173, s[42:43] offset:512
	s_waitcnt vmcnt(26)
	v_pk_fma_f32 v[86:87], v[86:87], v[130:131], v[236:237]
	v_pk_fma_f32 v[84:85], v[84:85], v[128:129], v[234:235]
	global_store_dwordx4 v174, v[84:87], s[60:61] offset:576
	global_load_dwordx4 v[234:237], v173, s[42:43] offset:576
	v_add_u32_e32 v174, 0x10000, v174
	s_waitcnt vmcnt(27)
	v_pk_fma_f32 v[82:83], v[82:83], v[146:147], v[240:241]
	v_pk_fma_f32 v[80:81], v[80:81], v[144:145], v[238:239]
	global_store_dwordx4 v174, v[80:83], s[60:61]
	v_add_u32_e32 v173, 0x10000, v173
	global_load_dwordx4 v[238:241], v173, s[42:43]
	s_waitcnt vmcnt(28)
	v_pk_fma_f32 v[78:79], v[78:79], v[138:139], v[244:245]
	v_pk_fma_f32 v[76:77], v[76:77], v[136:137], v[242:243]
	global_store_dwordx4 v174, v[76:79], s[60:61] offset:64
	global_load_dwordx4 v[242:245], v173, s[42:43] offset:64
	s_waitcnt vmcnt(29)
	v_pk_fma_f32 v[74:75], v[74:75], v[134:135], v[248:249]
	v_pk_fma_f32 v[72:73], v[72:73], v[132:133], v[246:247]
	global_store_dwordx4 v174, v[72:75], s[60:61] offset:512
	global_load_dwordx4 v[246:249], v173, s[42:43] offset:512
	s_waitcnt vmcnt(30)
	v_pk_fma_f32 v[70:71], v[70:71], v[130:131], v[166:167]
	v_pk_fma_f32 v[68:69], v[68:69], v[128:129], v[164:165]
	global_store_dwordx4 v174, v[68:71], s[60:61] offset:576
	global_load_dwordx4 v[164:167], v173, s[42:43] offset:576
	v_add_u32_e32 v174, 0x50000, v174
	s_waitcnt vmcnt(30)
	v_pk_fma_f32 v[66:67], v[66:67], v[146:147], v[192:193]
	v_pk_fma_f32 v[64:65], v[64:65], v[144:145], v[190:191]
	global_store_dwordx4 v174, v[64:67], s[60:61]
	s_waitcnt vmcnt(29)
	v_pk_fma_f32 v[62:63], v[62:63], v[138:139], v[196:197]
	v_pk_fma_f32 v[60:61], v[60:61], v[136:137], v[194:195]
	global_store_dwordx4 v174, v[60:63], s[60:61] offset:64
	s_waitcnt vmcnt(28)
	v_pk_fma_f32 v[58:59], v[58:59], v[134:135], v[200:201]
	v_pk_fma_f32 v[56:57], v[56:57], v[132:133], v[198:199]
	global_store_dwordx4 v174, v[56:59], s[60:61] offset:512
	s_waitcnt vmcnt(27)
	v_pk_fma_f32 v[54:55], v[54:55], v[130:131], v[204:205]
	v_pk_fma_f32 v[52:53], v[52:53], v[128:129], v[202:203]
	global_store_dwordx4 v174, v[52:55], s[60:61] offset:576
	v_add_u32_e32 v174, 0x10000, v174
	s_waitcnt vmcnt(26)
	v_pk_fma_f32 v[50:51], v[50:51], v[146:147], v[208:209]
	v_pk_fma_f32 v[48:49], v[48:49], v[144:145], v[206:207]
	global_store_dwordx4 v174, v[48:51], s[60:61]
	s_waitcnt vmcnt(25)
	v_pk_fma_f32 v[46:47], v[46:47], v[138:139], v[212:213]
	v_pk_fma_f32 v[44:45], v[44:45], v[136:137], v[210:211]
	global_store_dwordx4 v174, v[44:47], s[60:61] offset:64
	s_waitcnt vmcnt(24)
	v_pk_fma_f32 v[42:43], v[42:43], v[134:135], v[216:217]
	v_pk_fma_f32 v[40:41], v[40:41], v[132:133], v[214:215]
	global_store_dwordx4 v174, v[40:43], s[60:61] offset:512
	s_waitcnt vmcnt(23)
	v_pk_fma_f32 v[38:39], v[38:39], v[130:131], v[220:221]
	v_pk_fma_f32 v[36:37], v[36:37], v[128:129], v[218:219]
	global_store_dwordx4 v174, v[36:39], s[60:61] offset:576
	v_add_u32_e32 v174, 0x10000, v174
	s_waitcnt vmcnt(22)
	v_pk_fma_f32 v[34:35], v[34:35], v[146:147], v[224:225]
	v_pk_fma_f32 v[32:33], v[32:33], v[144:145], v[222:223]
	global_store_dwordx4 v174, v[32:35], s[60:61]
	s_waitcnt vmcnt(21)
	v_pk_fma_f32 v[30:31], v[30:31], v[138:139], v[228:229]
	v_pk_fma_f32 v[28:29], v[28:29], v[136:137], v[226:227]
	global_store_dwordx4 v174, v[28:31], s[60:61] offset:64
	s_waitcnt vmcnt(20)
	v_pk_fma_f32 v[26:27], v[26:27], v[134:135], v[232:233]
	v_pk_fma_f32 v[24:25], v[24:25], v[132:133], v[230:231]
	global_store_dwordx4 v174, v[24:27], s[60:61] offset:512
	s_waitcnt vmcnt(19)
	v_pk_fma_f32 v[22:23], v[22:23], v[130:131], v[236:237]
	v_pk_fma_f32 v[20:21], v[20:21], v[128:129], v[234:235]
	global_store_dwordx4 v174, v[20:23], s[60:61] offset:576
	v_add_u32_e32 v174, 0x10000, v174
	s_waitcnt vmcnt(18)
	v_pk_fma_f32 v[18:19], v[18:19], v[146:147], v[240:241]
	v_pk_fma_f32 v[16:17], v[16:17], v[144:145], v[238:239]
	global_store_dwordx4 v174, v[16:19], s[60:61]
	s_waitcnt vmcnt(17)
	v_pk_fma_f32 v[14:15], v[14:15], v[138:139], v[244:245]
	v_pk_fma_f32 v[12:13], v[12:13], v[136:137], v[242:243]
	global_store_dwordx4 v174, v[12:15], s[60:61] offset:64
	s_waitcnt vmcnt(16)
	v_pk_fma_f32 v[10:11], v[10:11], v[134:135], v[248:249]
	v_pk_fma_f32 v[8:9], v[8:9], v[132:133], v[246:247]
	global_store_dwordx4 v174, v[8:11], s[60:61] offset:512
	s_waitcnt vmcnt(15)
	v_pk_fma_f32 v[6:7], v[6:7], v[130:131], v[166:167]
	v_pk_fma_f32 v[4:5], v[4:5], v[128:129], v[164:165]
	global_store_dwordx4 v174, v[4:7], s[60:61] offset:576
	s_mov_b64 s[10:11], -1
	s_cbranch_vccnz .LBB0_664
	s_andn2_b64 vcc, exec, s[44:45]
	s_cbranch_vccnz .LBB0_663
	s_barrier
	s_branch .LBB0_663
